# K-loop handoff variant: only s_setprio 1 moved before the pre-MFMA barrier and redundant lgkmcnt wait removed
# speedup vs baseline: 1.0020x; 1.0013x over previous
.LBB0_159:
	s_add_u32 s0, s22, 0xfff80080
	s_addc_u32 s1, s23, -1
	s_add_i32 s51, 0, 0x10000
	s_cmp_eq_u32 s50, 28
	s_cselect_b32 s27, s15, s1
	s_cselect_b32 s26, s46, s0
	v_add_u32_e32 v140, s51, v143
	s_cselect_b32 s25, s13, s49
	s_cselect_b32 s24, s47, s48
	s_add_i32 s0, 0, 0x14000
	ds_read_b128 v[146:149], v140
	ds_read_b128 v[150:153], v140 offset:1024
	ds_read_b128 v[154:157], v140 offset:2048
	ds_read_b128 v[158:161], v140 offset:3072
	v_add_u32_e32 v140, s0, v143
	ds_read_b128 v[162:165], v140
	ds_read_b128 v[166:169], v140 offset:1024
	ds_read_b128 v[170:173], v140 offset:2048
	ds_read_b128 v[174:177], v140 offset:3072
	v_lshl_add_u64 v[140:141], s[22:23], 0, v[136:137]
	s_add_i32 m0, s35, 0xc000
	ds_read_b128 v[178:181], v144
	ds_read_b128 v[182:185], v144 offset:1024
	ds_read_b128 v[192:195], v144 offset:2048
	ds_read_b128 v[196:199], v144 offset:3072
	ds_read_b128 v[200:203], v144 offset:4096
	ds_read_b128 v[204:207], v144 offset:5120
	ds_read_b128 v[208:211], v144 offset:6144
	ds_read_b128 v[212:215], v144 offset:7168
	global_load_lds_dwordx4 v[140:141], off
	v_lshl_add_u64 v[140:141], s[22:23], 0, v[138:139]
	s_add_i32 m0, s35, 0xe000
	s_nop 0
	global_load_lds_dwordx4 v[140:141], off
	s_waitcnt vmcnt(8)
	s_waitcnt lgkmcnt(0)
	s_setprio 1
	s_barrier

	v_mfma_f32_16x16x32_bf16 v[126:129], v[146:149], v[178:181], v[126:129]
	v_mfma_f32_16x16x32_bf16 v[118:121], v[154:157], v[178:181], v[118:121]
	v_mfma_f32_16x16x32_bf16 v[110:113], v[146:149], v[192:195], v[110:113]
	v_mfma_f32_16x16x32_bf16 v[102:105], v[154:157], v[192:195], v[102:105]
	v_mfma_f32_16x16x32_bf16 v[94:97], v[146:149], v[200:203], v[94:97]
	v_mfma_f32_16x16x32_bf16 v[86:89], v[154:157], v[200:203], v[86:89]
	v_mfma_f32_16x16x32_bf16 v[78:81], v[146:149], v[208:211], v[78:81]
	v_mfma_f32_16x16x32_bf16 v[70:73], v[154:157], v[208:211], v[70:73]
	v_mfma_f32_16x16x32_bf16 v[126:129], v[150:153], v[182:185], v[126:129]
	v_mfma_f32_16x16x32_bf16 v[118:121], v[158:161], v[182:185], v[118:121]
	v_mfma_f32_16x16x32_bf16 v[110:113], v[150:153], v[196:199], v[110:113]
	v_mfma_f32_16x16x32_bf16 v[102:105], v[158:161], v[196:199], v[102:105]
	v_mfma_f32_16x16x32_bf16 v[94:97], v[150:153], v[204:207], v[94:97]
	v_mfma_f32_16x16x32_bf16 v[86:89], v[158:161], v[204:207], v[86:89]
	v_mfma_f32_16x16x32_bf16 v[78:81], v[150:153], v[212:215], v[78:81]
	v_mfma_f32_16x16x32_bf16 v[70:73], v[158:161], v[212:215], v[70:73]
	s_setprio 0
	s_setprio 1
	v_mfma_f32_16x16x32_bf16 v[122:125], v[162:165], v[178:181], v[122:125]
	v_mfma_f32_16x16x32_bf16 v[114:117], v[170:173], v[178:181], v[114:117]
	v_mfma_f32_16x16x32_bf16 v[106:109], v[162:165], v[192:195], v[106:109]
	v_mfma_f32_16x16x32_bf16 v[98:101], v[170:173], v[192:195], v[98:101]
	v_mfma_f32_16x16x32_bf16 v[90:93], v[162:165], v[200:203], v[90:93]
	v_mfma_f32_16x16x32_bf16 v[82:85], v[170:173], v[200:203], v[82:85]
	v_mfma_f32_16x16x32_bf16 v[74:77], v[162:165], v[208:211], v[74:77]
	v_mfma_f32_16x16x32_bf16 v[66:69], v[170:173], v[208:211], v[66:69]
	v_mfma_f32_16x16x32_bf16 v[122:125], v[166:169], v[182:185], v[122:125]
	v_mfma_f32_16x16x32_bf16 v[114:117], v[174:177], v[182:185], v[114:117]
	v_mfma_f32_16x16x32_bf16 v[106:109], v[166:169], v[196:199], v[106:109]
	v_mfma_f32_16x16x32_bf16 v[98:101], v[174:177], v[196:199], v[98:101]
	v_mfma_f32_16x16x32_bf16 v[90:93], v[166:169], v[204:207], v[90:93]
	v_mfma_f32_16x16x32_bf16 v[82:85], v[174:177], v[204:207], v[82:85]
	v_mfma_f32_16x16x32_bf16 v[74:77], v[166:169], v[212:215], v[74:77]
	v_mfma_f32_16x16x32_bf16 v[66:69], v[174:177], v[212:215], v[66:69]
	s_setprio 0
	s_barrier
	s_add_i32 s1, s51, s31
	v_lshl_add_u64 v[140:141], s[24:25], 0, v[186:187]
	s_mov_b32 m0, s1
	ds_read_b128 v[178:181], v144 offset:16384
	ds_read_b128 v[182:185], v144 offset:17408
	ds_read_b128 v[192:195], v144 offset:18432
	ds_read_b128 v[196:199], v144 offset:19456
	ds_read_b128 v[200:203], v144 offset:20480
	ds_read_b128 v[204:207], v144 offset:21504
	ds_read_b128 v[208:211], v144 offset:22528
	ds_read_b128 v[212:215], v144 offset:23552
	global_load_lds_dwordx4 v[140:141], off
	s_add_i32 m0, s1, 0x2000
	s_add_u32 s52, s24, 0x80000
	v_lshl_add_u64 v[216:217], s[24:25], 0, v[130:131]
	s_addc_u32 s53, s25, 0
	s_add_i32 s0, s0, s31
	global_load_lds_dwordx4 v[216:217], off
	v_lshl_add_u64 v[218:219], s[52:53], 0, v[186:187]
	s_mov_b32 m0, s0
	v_lshl_add_u64 v[220:221], s[26:27], 0, v[132:133]
	global_load_lds_dwordx4 v[218:219], off
	v_lshl_add_u64 v[218:219], s[52:53], 0, v[130:131]
	s_add_i32 m0, s0, 0x2000
	s_nop 0
	global_load_lds_dwordx4 v[218:219], off
	v_lshl_add_u64 v[218:219], s[26:27], 0, v[134:135]
	s_mov_b32 m0, s35
	s_nop 0
	global_load_lds_dwordx4 v[218:219], off
	s_mov_b32 m0, s36
	s_nop 0
	global_load_lds_dwordx4 v[220:221], off
	s_waitcnt vmcnt(8)
	s_waitcnt lgkmcnt(0)
	s_setprio 1
	s_barrier

	v_mfma_f32_16x16x32_bf16 v[62:65], v[146:149], v[178:181], v[62:65]
	v_mfma_f32_16x16x32_bf16 v[54:57], v[154:157], v[178:181], v[54:57]
	v_mfma_f32_16x16x32_bf16 v[46:49], v[146:149], v[192:195], v[46:49]
	v_mfma_f32_16x16x32_bf16 v[38:41], v[154:157], v[192:195], v[38:41]
	v_mfma_f32_16x16x32_bf16 v[30:33], v[146:149], v[200:203], v[30:33]
	v_mfma_f32_16x16x32_bf16 v[22:25], v[154:157], v[200:203], v[22:25]
	v_mfma_f32_16x16x32_bf16 v[14:17], v[146:149], v[208:211], v[14:17]
	v_mfma_f32_16x16x32_bf16 v[6:9], v[154:157], v[208:211], v[6:9]
	v_mfma_f32_16x16x32_bf16 v[62:65], v[150:153], v[182:185], v[62:65]
	v_mfma_f32_16x16x32_bf16 v[54:57], v[158:161], v[182:185], v[54:57]
	v_mfma_f32_16x16x32_bf16 v[46:49], v[150:153], v[196:199], v[46:49]
	v_mfma_f32_16x16x32_bf16 v[38:41], v[158:161], v[196:199], v[38:41]
	v_mfma_f32_16x16x32_bf16 v[30:33], v[150:153], v[204:207], v[30:33]
	v_mfma_f32_16x16x32_bf16 v[22:25], v[158:161], v[204:207], v[22:25]
	v_mfma_f32_16x16x32_bf16 v[14:17], v[150:153], v[212:215], v[14:17]
	v_mfma_f32_16x16x32_bf16 v[6:9], v[158:161], v[212:215], v[6:9]
	s_setprio 0
	s_setprio 1
	v_mfma_f32_16x16x32_bf16 v[58:61], v[162:165], v[178:181], v[58:61]
	v_mfma_f32_16x16x32_bf16 v[50:53], v[170:173], v[178:181], v[50:53]
	v_mfma_f32_16x16x32_bf16 v[42:45], v[162:165], v[192:195], v[42:45]
	v_mfma_f32_16x16x32_bf16 v[34:37], v[170:173], v[192:195], v[34:37]
	v_mfma_f32_16x16x32_bf16 v[26:29], v[162:165], v[200:203], v[26:29]
	v_mfma_f32_16x16x32_bf16 v[18:21], v[170:173], v[200:203], v[18:21]
	v_mfma_f32_16x16x32_bf16 v[10:13], v[162:165], v[208:211], v[10:13]
	v_mfma_f32_16x16x32_bf16 v[2:5], v[170:173], v[208:211], v[2:5]
	v_mfma_f32_16x16x32_bf16 v[58:61], v[166:169], v[182:185], v[58:61]
	v_mfma_f32_16x16x32_bf16 v[50:53], v[174:177], v[182:185], v[50:53]
	v_mfma_f32_16x16x32_bf16 v[42:45], v[166:169], v[196:199], v[42:45]
	v_mfma_f32_16x16x32_bf16 v[34:37], v[174:177], v[196:199], v[34:37]
	v_mfma_f32_16x16x32_bf16 v[26:29], v[166:169], v[204:207], v[26:29]
	v_mfma_f32_16x16x32_bf16 v[18:21], v[174:177], v[204:207], v[18:21]
	v_mfma_f32_16x16x32_bf16 v[10:13], v[166:169], v[212:215], v[10:13]
	v_mfma_f32_16x16x32_bf16 v[2:5], v[174:177], v[212:215], v[2:5]
	s_setprio 0
	s_barrier
	s_add_i32 s0, 0, 0x18000
	v_add_u32_e32 v145, s0, v143
	s_add_i32 s1, 0, 0x1c000
	ds_read_b128 v[146:149], v145
	ds_read_b128 v[150:153], v145 offset:1024
	ds_read_b128 v[154:157], v145 offset:2048
	ds_read_b128 v[158:161], v145 offset:3072
	v_add_u32_e32 v145, s1, v143
	ds_read_b128 v[162:165], v145
	ds_read_b128 v[166:169], v145 offset:1024
	ds_read_b128 v[170:173], v145 offset:2048
	ds_read_b128 v[174:177], v145 offset:3072
	s_add_u32 s26, s26, 0x80000
	s_addc_u32 s27, s27, 0
	s_mov_b32 m0, s37
	v_lshl_add_u64 v[222:223], s[26:27], 0, v[134:135]
	ds_read_b128 v[178:181], v144 offset:32768
	ds_read_b128 v[182:185], v144 offset:33792
	ds_read_b128 v[192:195], v144 offset:34816
	ds_read_b128 v[196:199], v144 offset:35840
	ds_read_b128 v[200:203], v144 offset:36864
	ds_read_b128 v[204:207], v144 offset:37888
	ds_read_b128 v[208:211], v144 offset:38912
	ds_read_b128 v[212:215], v144 offset:39936
	global_load_lds_dwordx4 v[222:223], off
	v_lshl_add_u64 v[222:223], s[26:27], 0, v[132:133]
	s_mov_b32 m0, s38
	s_nop 0
	global_load_lds_dwordx4 v[222:223], off
	s_waitcnt vmcnt(8)
	s_waitcnt lgkmcnt(0)
	s_setprio 1
	s_barrier

	v_mfma_f32_16x16x32_bf16 v[126:129], v[146:149], v[178:181], v[126:129]
	v_mfma_f32_16x16x32_bf16 v[118:121], v[154:157], v[178:181], v[118:121]
	v_mfma_f32_16x16x32_bf16 v[110:113], v[146:149], v[192:195], v[110:113]
	v_mfma_f32_16x16x32_bf16 v[102:105], v[154:157], v[192:195], v[102:105]
	v_mfma_f32_16x16x32_bf16 v[94:97], v[146:149], v[200:203], v[94:97]
	v_mfma_f32_16x16x32_bf16 v[86:89], v[154:157], v[200:203], v[86:89]
	v_mfma_f32_16x16x32_bf16 v[78:81], v[146:149], v[208:211], v[78:81]
	v_mfma_f32_16x16x32_bf16 v[70:73], v[154:157], v[208:211], v[70:73]
	v_mfma_f32_16x16x32_bf16 v[126:129], v[150:153], v[182:185], v[126:129]
	v_mfma_f32_16x16x32_bf16 v[118:121], v[158:161], v[182:185], v[118:121]
	v_mfma_f32_16x16x32_bf16 v[110:113], v[150:153], v[196:199], v[110:113]
	v_mfma_f32_16x16x32_bf16 v[102:105], v[158:161], v[196:199], v[102:105]
	v_mfma_f32_16x16x32_bf16 v[94:97], v[150:153], v[204:207], v[94:97]
	v_mfma_f32_16x16x32_bf16 v[86:89], v[158:161], v[204:207], v[86:89]
	v_mfma_f32_16x16x32_bf16 v[78:81], v[150:153], v[212:215], v[78:81]
	v_mfma_f32_16x16x32_bf16 v[70:73], v[158:161], v[212:215], v[70:73]
	s_setprio 0
	s_setprio 1
	v_mfma_f32_16x16x32_bf16 v[122:125], v[162:165], v[178:181], v[122:125]
	v_mfma_f32_16x16x32_bf16 v[114:117], v[170:173], v[178:181], v[114:117]
	v_mfma_f32_16x16x32_bf16 v[106:109], v[162:165], v[192:195], v[106:109]
	v_mfma_f32_16x16x32_bf16 v[98:101], v[170:173], v[192:195], v[98:101]
	v_mfma_f32_16x16x32_bf16 v[90:93], v[162:165], v[200:203], v[90:93]
	v_mfma_f32_16x16x32_bf16 v[82:85], v[170:173], v[200:203], v[82:85]
	v_mfma_f32_16x16x32_bf16 v[74:77], v[162:165], v[208:211], v[74:77]
	v_mfma_f32_16x16x32_bf16 v[66:69], v[170:173], v[208:211], v[66:69]
	v_mfma_f32_16x16x32_bf16 v[122:125], v[166:169], v[182:185], v[122:125]
	v_mfma_f32_16x16x32_bf16 v[114:117], v[174:177], v[182:185], v[114:117]
	v_mfma_f32_16x16x32_bf16 v[106:109], v[166:169], v[196:199], v[106:109]
	v_mfma_f32_16x16x32_bf16 v[98:101], v[174:177], v[196:199], v[98:101]
	v_mfma_f32_16x16x32_bf16 v[90:93], v[166:169], v[204:207], v[90:93]
	v_mfma_f32_16x16x32_bf16 v[82:85], v[174:177], v[204:207], v[82:85]
	v_mfma_f32_16x16x32_bf16 v[74:77], v[166:169], v[212:215], v[74:77]
	v_mfma_f32_16x16x32_bf16 v[66:69], v[174:177], v[212:215], v[66:69]
	s_setprio 0
	s_barrier
	s_add_i32 s0, s0, s31
	v_lshl_add_u64 v[140:141], v[140:141], 0, s[84:85]
	s_mov_b32 m0, s0
	ds_read_b128 v[178:181], v144 offset:49152
	ds_read_b128 v[182:185], v144 offset:50176
	ds_read_b128 v[192:195], v144 offset:51200
	ds_read_b128 v[196:199], v144 offset:52224
	ds_read_b128 v[200:203], v144 offset:53248
	ds_read_b128 v[204:207], v144 offset:54272
	ds_read_b128 v[208:211], v144 offset:55296
	ds_read_b128 v[212:215], v144 offset:56320
	global_load_lds_dwordx4 v[140:141], off
	s_add_i32 m0, s0, 0x2000
	s_add_u32 s24, s24, 0x80080
	v_lshl_add_u64 v[140:141], v[216:217], 0, s[84:85]
	s_addc_u32 s25, s25, 0
	s_add_i32 s0, s1, s31
	global_load_lds_dwordx4 v[140:141], off
	v_lshl_add_u64 v[140:141], s[24:25], 0, v[186:187]
	s_mov_b32 m0, s0
	s_nop 0
	global_load_lds_dwordx4 v[140:141], off
	v_lshl_add_u64 v[140:141], s[24:25], 0, v[130:131]
	s_add_i32 m0, s0, 0x2000
	s_nop 0
	global_load_lds_dwordx4 v[140:141], off
	v_lshl_add_u64 v[140:141], v[218:219], 0, s[84:85]
	s_mov_b32 m0, s39
	s_nop 0
	global_load_lds_dwordx4 v[140:141], off
	v_lshl_add_u64 v[140:141], v[220:221], 0, s[84:85]
	s_mov_b32 m0, s40
	s_nop 0
	global_load_lds_dwordx4 v[140:141], off
	s_waitcnt vmcnt(8)
	s_waitcnt lgkmcnt(0)
	s_setprio 1
	s_barrier

	v_mfma_f32_16x16x32_bf16 v[62:65], v[146:149], v[178:181], v[62:65]
	v_mfma_f32_16x16x32_bf16 v[54:57], v[154:157], v[178:181], v[54:57]
	v_mfma_f32_16x16x32_bf16 v[46:49], v[146:149], v[192:195], v[46:49]
	v_mfma_f32_16x16x32_bf16 v[38:41], v[154:157], v[192:195], v[38:41]
	v_mfma_f32_16x16x32_bf16 v[30:33], v[146:149], v[200:203], v[30:33]
	v_mfma_f32_16x16x32_bf16 v[22:25], v[154:157], v[200:203], v[22:25]
	v_mfma_f32_16x16x32_bf16 v[14:17], v[146:149], v[208:211], v[14:17]
	v_mfma_f32_16x16x32_bf16 v[6:9], v[154:157], v[208:211], v[6:9]
	v_mfma_f32_16x16x32_bf16 v[62:65], v[150:153], v[182:185], v[62:65]
	v_mfma_f32_16x16x32_bf16 v[54:57], v[158:161], v[182:185], v[54:57]
	v_mfma_f32_16x16x32_bf16 v[46:49], v[150:153], v[196:199], v[46:49]
	v_mfma_f32_16x16x32_bf16 v[38:41], v[158:161], v[196:199], v[38:41]
	v_mfma_f32_16x16x32_bf16 v[30:33], v[150:153], v[204:207], v[30:33]
	v_mfma_f32_16x16x32_bf16 v[22:25], v[158:161], v[204:207], v[22:25]
	v_mfma_f32_16x16x32_bf16 v[14:17], v[150:153], v[212:215], v[14:17]
	v_mfma_f32_16x16x32_bf16 v[6:9], v[158:161], v[212:215], v[6:9]
	s_setprio 0
	s_setprio 1
	v_mfma_f32_16x16x32_bf16 v[58:61], v[162:165], v[178:181], v[58:61]
	v_mfma_f32_16x16x32_bf16 v[50:53], v[170:173], v[178:181], v[50:53]
	v_mfma_f32_16x16x32_bf16 v[42:45], v[162:165], v[192:195], v[42:45]
	v_mfma_f32_16x16x32_bf16 v[34:37], v[170:173], v[192:195], v[34:37]
	v_mfma_f32_16x16x32_bf16 v[26:29], v[162:165], v[200:203], v[26:29]
	v_mfma_f32_16x16x32_bf16 v[18:21], v[170:173], v[200:203], v[18:21]
	v_mfma_f32_16x16x32_bf16 v[10:13], v[162:165], v[208:211], v[10:13]
	v_mfma_f32_16x16x32_bf16 v[2:5], v[170:173], v[208:211], v[2:5]
	v_mfma_f32_16x16x32_bf16 v[58:61], v[166:169], v[182:185], v[58:61]
	v_mfma_f32_16x16x32_bf16 v[50:53], v[174:177], v[182:185], v[50:53]
	v_mfma_f32_16x16x32_bf16 v[42:45], v[166:169], v[196:199], v[42:45]
	v_mfma_f32_16x16x32_bf16 v[34:37], v[174:177], v[196:199], v[34:37]
	v_mfma_f32_16x16x32_bf16 v[26:29], v[166:169], v[204:207], v[26:29]
	v_mfma_f32_16x16x32_bf16 v[18:21], v[174:177], v[204:207], v[18:21]
	v_mfma_f32_16x16x32_bf16 v[10:13], v[166:169], v[212:215], v[10:13]
	v_mfma_f32_16x16x32_bf16 v[2:5], v[174:177], v[212:215], v[2:5]
	s_setprio 0
	s_barrier
	s_add_i32 s50, s50, 2
	s_add_u32 s22, s22, 0x100
	s_addc_u32 s23, s23, 0
	s_add_u32 s48, s48, 0x100
	s_addc_u32 s49, s49, 0
	s_cmp_gt_u32 s50, 29
	s_cbranch_scc0 .LBB0_159
	s_and_b64 vcc, exec, s[10:11]
	s_cbranch_vccz .LBB0_162
	s_barrier

.LBB0_243:
	s_add_u32 s22, s20, 0x100
	s_addc_u32 s23, s21, 0
	s_add_i32 s0, 0, 0x10000
	s_cmpk_eq_i32 s51, 0x54
	s_cselect_b32 s27, s7, s23
	s_cselect_b32 s26, s6, s22
	s_cselect_b32 s25, s19, s50
	s_cselect_b32 s24, s18, s49
	s_add_i32 s1, 0, 0x14000
	v_add_u32_e32 v126, s0, v237
	v_add_u32_e32 v158, s1, v237
	ds_read_b128 v[90:93], v126
	ds_read_b128 v[102:105], v126 offset:1024
	ds_read_b128 v[114:117], v126 offset:2048
	ds_read_b128 v[126:129], v126 offset:3072
	ds_read_b128 v[138:141], v158
	ds_read_b128 v[142:145], v158 offset:1024
	ds_read_b128 v[154:157], v158 offset:2048
	ds_read_b128 v[158:161], v158 offset:3072
	v_lshl_add_u64 v[210:211], s[20:21], 0, v[198:199]
	s_add_i32 m0, s34, 0xc000
	ds_read_b128 v[162:165], v238
	ds_read_b128 v[166:169], v238 offset:1024
	ds_read_b128 v[170:173], v238 offset:2048
	ds_read_b128 v[174:177], v238 offset:3072
	ds_read_b128 v[178:181], v238 offset:4096
	ds_read_b128 v[182:185], v238 offset:5120
	ds_read_b128 v[202:205], v238 offset:6144
	ds_read_b128 v[206:209], v238 offset:7168
	global_load_lds_dwordx4 v[210:211], off
	v_lshl_add_u64 v[210:211], s[20:21], 0, v[200:201]
	s_add_i32 m0, s34, 0xe000
	s_nop 0
	global_load_lds_dwordx4 v[210:211], off
	s_waitcnt vmcnt(8)
	s_waitcnt lgkmcnt(0)
	s_setprio 1
	s_barrier

	v_mfma_f32_16x16x32_bf16 v[150:153], v[90:93], v[162:165], v[150:153]
	v_mfma_f32_16x16x32_bf16 v[146:149], v[114:117], v[162:165], v[146:149]
	v_mfma_f32_16x16x32_bf16 v[122:125], v[90:93], v[170:173], v[122:125]
	v_mfma_f32_16x16x32_bf16 v[118:121], v[114:117], v[170:173], v[118:121]
	v_mfma_f32_16x16x32_bf16 v[98:101], v[90:93], v[178:181], v[98:101]
	v_mfma_f32_16x16x32_bf16 v[94:97], v[114:117], v[178:181], v[94:97]
	v_mfma_f32_16x16x32_bf16 v[78:81], v[90:93], v[202:205], v[78:81]
	v_mfma_f32_16x16x32_bf16 v[74:77], v[114:117], v[202:205], v[74:77]
	v_mfma_f32_16x16x32_bf16 v[150:153], v[102:105], v[166:169], v[150:153]
	v_mfma_f32_16x16x32_bf16 v[146:149], v[126:129], v[166:169], v[146:149]
	v_mfma_f32_16x16x32_bf16 v[122:125], v[102:105], v[174:177], v[122:125]
	v_mfma_f32_16x16x32_bf16 v[118:121], v[126:129], v[174:177], v[118:121]
	v_mfma_f32_16x16x32_bf16 v[98:101], v[102:105], v[182:185], v[98:101]
	v_mfma_f32_16x16x32_bf16 v[94:97], v[126:129], v[182:185], v[94:97]
	v_mfma_f32_16x16x32_bf16 v[78:81], v[102:105], v[206:209], v[78:81]
	v_mfma_f32_16x16x32_bf16 v[74:77], v[126:129], v[206:209], v[74:77]
	s_setprio 0
	s_setprio 1
	v_mfma_f32_16x16x32_bf16 v[134:137], v[138:141], v[162:165], v[134:137]
	v_mfma_f32_16x16x32_bf16 v[130:133], v[154:157], v[162:165], v[130:133]
	v_mfma_f32_16x16x32_bf16 v[110:113], v[138:141], v[170:173], v[110:113]
	v_mfma_f32_16x16x32_bf16 v[106:109], v[154:157], v[170:173], v[106:109]
	v_mfma_f32_16x16x32_bf16 v[86:89], v[138:141], v[178:181], v[86:89]
	v_mfma_f32_16x16x32_bf16 v[82:85], v[154:157], v[178:181], v[82:85]
	v_mfma_f32_16x16x32_bf16 v[70:73], v[138:141], v[202:205], v[70:73]
	v_mfma_f32_16x16x32_bf16 v[66:69], v[154:157], v[202:205], v[66:69]
	v_mfma_f32_16x16x32_bf16 v[134:137], v[142:145], v[166:169], v[134:137]
	v_mfma_f32_16x16x32_bf16 v[130:133], v[158:161], v[166:169], v[130:133]
	v_mfma_f32_16x16x32_bf16 v[110:113], v[142:145], v[174:177], v[110:113]
	v_mfma_f32_16x16x32_bf16 v[106:109], v[158:161], v[174:177], v[106:109]
	v_mfma_f32_16x16x32_bf16 v[86:89], v[142:145], v[182:185], v[86:89]
	v_mfma_f32_16x16x32_bf16 v[82:85], v[158:161], v[182:185], v[82:85]
	v_mfma_f32_16x16x32_bf16 v[70:73], v[142:145], v[206:209], v[70:73]
	v_mfma_f32_16x16x32_bf16 v[66:69], v[158:161], v[206:209], v[66:69]
	s_setprio 0
	s_barrier
	s_add_i32 s0, s0, s31
	v_lshl_add_u64 v[210:211], s[24:25], 0, v[186:187]
	s_mov_b32 m0, s0
	ds_read_b128 v[162:165], v238 offset:16384
	ds_read_b128 v[166:169], v238 offset:17408
	ds_read_b128 v[170:173], v238 offset:18432
	ds_read_b128 v[174:177], v238 offset:19456
	ds_read_b128 v[178:181], v238 offset:20480
	ds_read_b128 v[182:185], v238 offset:21504
	ds_read_b128 v[202:205], v238 offset:22528
	ds_read_b128 v[206:209], v238 offset:23552
	global_load_lds_dwordx4 v[210:211], off
	s_add_i32 m0, s0, 0x2000
	s_add_u32 s20, s24, 0x160000
	v_lshl_add_u64 v[212:213], s[24:25], 0, v[196:197]
	s_addc_u32 s21, s25, 0
	s_add_i32 s0, s1, s31
	global_load_lds_dwordx4 v[212:213], off
	v_lshl_add_u64 v[214:215], s[20:21], 0, v[186:187]
	s_mov_b32 m0, s0
	v_lshl_add_u64 v[216:217], s[26:27], 0, v[194:195]
	global_load_lds_dwordx4 v[214:215], off
	v_lshl_add_u64 v[214:215], s[20:21], 0, v[196:197]
	s_add_i32 m0, s0, 0x2000
	s_nop 0
	global_load_lds_dwordx4 v[214:215], off
	v_lshl_add_u64 v[214:215], s[26:27], 0, v[192:193]
	s_mov_b32 m0, s34
	s_nop 0
	global_load_lds_dwordx4 v[214:215], off
	s_mov_b32 m0, s35
	s_nop 0
	global_load_lds_dwordx4 v[216:217], off
	s_waitcnt vmcnt(8)
	s_waitcnt lgkmcnt(0)
	s_setprio 1
	s_barrier

	v_mfma_f32_16x16x32_bf16 v[62:65], v[90:93], v[162:165], v[62:65]
	v_mfma_f32_16x16x32_bf16 v[58:61], v[114:117], v[162:165], v[58:61]
	v_mfma_f32_16x16x32_bf16 v[46:49], v[90:93], v[170:173], v[46:49]
	v_mfma_f32_16x16x32_bf16 v[42:45], v[114:117], v[170:173], v[42:45]
	v_mfma_f32_16x16x32_bf16 v[30:33], v[90:93], v[178:181], v[30:33]
	v_mfma_f32_16x16x32_bf16 v[26:29], v[114:117], v[178:181], v[26:29]
	v_mfma_f32_16x16x32_bf16 v[14:17], v[90:93], v[202:205], v[14:17]
	v_mfma_f32_16x16x32_bf16 v[10:13], v[114:117], v[202:205], v[10:13]
	v_mfma_f32_16x16x32_bf16 v[62:65], v[102:105], v[166:169], v[62:65]
	v_mfma_f32_16x16x32_bf16 v[58:61], v[126:129], v[166:169], v[58:61]
	v_mfma_f32_16x16x32_bf16 v[46:49], v[102:105], v[174:177], v[46:49]
	v_mfma_f32_16x16x32_bf16 v[42:45], v[126:129], v[174:177], v[42:45]
	v_mfma_f32_16x16x32_bf16 v[30:33], v[102:105], v[182:185], v[30:33]
	v_mfma_f32_16x16x32_bf16 v[26:29], v[126:129], v[182:185], v[26:29]
	v_mfma_f32_16x16x32_bf16 v[14:17], v[102:105], v[206:209], v[14:17]
	v_mfma_f32_16x16x32_bf16 v[10:13], v[126:129], v[206:209], v[10:13]
	s_setprio 0
	s_setprio 1
	v_mfma_f32_16x16x32_bf16 v[54:57], v[138:141], v[162:165], v[54:57]
	v_mfma_f32_16x16x32_bf16 v[50:53], v[154:157], v[162:165], v[50:53]
	v_mfma_f32_16x16x32_bf16 v[38:41], v[138:141], v[170:173], v[38:41]
	v_mfma_f32_16x16x32_bf16 v[34:37], v[154:157], v[170:173], v[34:37]
	v_mfma_f32_16x16x32_bf16 v[22:25], v[138:141], v[178:181], v[22:25]
	v_mfma_f32_16x16x32_bf16 v[18:21], v[154:157], v[178:181], v[18:21]
	v_mfma_f32_16x16x32_bf16 v[6:9], v[138:141], v[202:205], v[6:9]
	v_mfma_f32_16x16x32_bf16 v[2:5], v[154:157], v[202:205], v[2:5]
	v_mfma_f32_16x16x32_bf16 v[54:57], v[142:145], v[166:169], v[54:57]
	v_mfma_f32_16x16x32_bf16 v[50:53], v[158:161], v[166:169], v[50:53]
	v_mfma_f32_16x16x32_bf16 v[38:41], v[142:145], v[174:177], v[38:41]
	v_mfma_f32_16x16x32_bf16 v[34:37], v[158:161], v[174:177], v[34:37]
	v_mfma_f32_16x16x32_bf16 v[22:25], v[142:145], v[182:185], v[22:25]
	v_mfma_f32_16x16x32_bf16 v[18:21], v[158:161], v[182:185], v[18:21]
	v_mfma_f32_16x16x32_bf16 v[6:9], v[142:145], v[206:209], v[6:9]
	v_mfma_f32_16x16x32_bf16 v[2:5], v[158:161], v[206:209], v[2:5]
	s_setprio 0
	s_barrier
	s_add_i32 s0, 0, 0x18000
	s_add_i32 s1, 0, 0x1c000
	v_add_u32_e32 v126, s0, v237
	v_add_u32_e32 v158, s1, v237
	ds_read_b128 v[90:93], v126
	ds_read_b128 v[102:105], v126 offset:1024
	ds_read_b128 v[114:117], v126 offset:2048
	ds_read_b128 v[126:129], v126 offset:3072
	ds_read_b128 v[138:141], v158
	ds_read_b128 v[142:145], v158 offset:1024
	ds_read_b128 v[154:157], v158 offset:2048
	ds_read_b128 v[158:161], v158 offset:3072
	s_add_u32 s20, s26, 0x160000
	s_addc_u32 s21, s27, 0
	s_mov_b32 m0, s36
	v_lshl_add_u64 v[218:219], s[20:21], 0, v[192:193]
	ds_read_b128 v[162:165], v238 offset:32768
	ds_read_b128 v[166:169], v238 offset:33792
	ds_read_b128 v[170:173], v238 offset:34816
	ds_read_b128 v[174:177], v238 offset:35840
	ds_read_b128 v[178:181], v238 offset:36864
	ds_read_b128 v[182:185], v238 offset:37888
	ds_read_b128 v[202:205], v238 offset:38912
	ds_read_b128 v[206:209], v238 offset:39936
	global_load_lds_dwordx4 v[218:219], off
	v_lshl_add_u64 v[218:219], s[20:21], 0, v[194:195]
	s_mov_b32 m0, s37
	s_nop 0
	global_load_lds_dwordx4 v[218:219], off
	s_waitcnt vmcnt(8)
	s_waitcnt lgkmcnt(0)
	s_setprio 1
	s_barrier

	v_mfma_f32_16x16x32_bf16 v[150:153], v[90:93], v[162:165], v[150:153]
	v_mfma_f32_16x16x32_bf16 v[146:149], v[114:117], v[162:165], v[146:149]
	v_mfma_f32_16x16x32_bf16 v[122:125], v[90:93], v[170:173], v[122:125]
	v_mfma_f32_16x16x32_bf16 v[118:121], v[114:117], v[170:173], v[118:121]
	v_mfma_f32_16x16x32_bf16 v[98:101], v[90:93], v[178:181], v[98:101]
	v_mfma_f32_16x16x32_bf16 v[94:97], v[114:117], v[178:181], v[94:97]
	v_mfma_f32_16x16x32_bf16 v[78:81], v[90:93], v[202:205], v[78:81]
	v_mfma_f32_16x16x32_bf16 v[74:77], v[114:117], v[202:205], v[74:77]
	v_mfma_f32_16x16x32_bf16 v[150:153], v[102:105], v[166:169], v[150:153]
	v_mfma_f32_16x16x32_bf16 v[146:149], v[126:129], v[166:169], v[146:149]
	v_mfma_f32_16x16x32_bf16 v[122:125], v[102:105], v[174:177], v[122:125]
	v_mfma_f32_16x16x32_bf16 v[118:121], v[126:129], v[174:177], v[118:121]
	v_mfma_f32_16x16x32_bf16 v[98:101], v[102:105], v[182:185], v[98:101]
	v_mfma_f32_16x16x32_bf16 v[94:97], v[126:129], v[182:185], v[94:97]
	v_mfma_f32_16x16x32_bf16 v[78:81], v[102:105], v[206:209], v[78:81]
	v_mfma_f32_16x16x32_bf16 v[74:77], v[126:129], v[206:209], v[74:77]
	s_setprio 0
	s_setprio 1
	v_mfma_f32_16x16x32_bf16 v[134:137], v[138:141], v[162:165], v[134:137]
	v_mfma_f32_16x16x32_bf16 v[130:133], v[154:157], v[162:165], v[130:133]
	v_mfma_f32_16x16x32_bf16 v[110:113], v[138:141], v[170:173], v[110:113]
	v_mfma_f32_16x16x32_bf16 v[106:109], v[154:157], v[170:173], v[106:109]
	v_mfma_f32_16x16x32_bf16 v[86:89], v[138:141], v[178:181], v[86:89]
	v_mfma_f32_16x16x32_bf16 v[82:85], v[154:157], v[178:181], v[82:85]
	v_mfma_f32_16x16x32_bf16 v[70:73], v[138:141], v[202:205], v[70:73]
	v_mfma_f32_16x16x32_bf16 v[66:69], v[154:157], v[202:205], v[66:69]
	v_mfma_f32_16x16x32_bf16 v[134:137], v[142:145], v[166:169], v[134:137]
	v_mfma_f32_16x16x32_bf16 v[130:133], v[158:161], v[166:169], v[130:133]
	v_mfma_f32_16x16x32_bf16 v[110:113], v[142:145], v[174:177], v[110:113]
	v_mfma_f32_16x16x32_bf16 v[106:109], v[158:161], v[174:177], v[106:109]
	v_mfma_f32_16x16x32_bf16 v[86:89], v[142:145], v[182:185], v[86:89]
	v_mfma_f32_16x16x32_bf16 v[82:85], v[158:161], v[182:185], v[82:85]
	v_mfma_f32_16x16x32_bf16 v[70:73], v[142:145], v[206:209], v[70:73]
	v_mfma_f32_16x16x32_bf16 v[66:69], v[158:161], v[206:209], v[66:69]
	s_setprio 0
	s_barrier
	s_add_i32 s0, s0, s31
	v_lshl_add_u64 v[210:211], v[210:211], 0, s[84:85]
	s_mov_b32 m0, s0
	ds_read_b128 v[162:165], v238 offset:49152
	ds_read_b128 v[166:169], v238 offset:50176
	ds_read_b128 v[170:173], v238 offset:51200
	ds_read_b128 v[174:177], v238 offset:52224
	ds_read_b128 v[178:181], v238 offset:53248
	ds_read_b128 v[182:185], v238 offset:54272
	ds_read_b128 v[202:205], v238 offset:55296
	ds_read_b128 v[206:209], v238 offset:56320
	global_load_lds_dwordx4 v[210:211], off
	s_add_i32 m0, s0, 0x2000
	s_add_u32 s20, s24, 0x160080
	v_lshl_add_u64 v[210:211], v[212:213], 0, s[84:85]
	s_addc_u32 s21, s25, 0
	s_add_i32 s0, s1, s31
	global_load_lds_dwordx4 v[210:211], off
	v_lshl_add_u64 v[210:211], s[20:21], 0, v[186:187]
	s_mov_b32 m0, s0
	s_nop 0
	global_load_lds_dwordx4 v[210:211], off
	v_lshl_add_u64 v[210:211], s[20:21], 0, v[196:197]
	s_add_i32 m0, s0, 0x2000
	s_nop 0
	global_load_lds_dwordx4 v[210:211], off
	v_lshl_add_u64 v[210:211], v[214:215], 0, s[84:85]
	s_mov_b32 m0, s41
	s_nop 0
	global_load_lds_dwordx4 v[210:211], off
	v_lshl_add_u64 v[210:211], v[216:217], 0, s[84:85]
	s_mov_b32 m0, s42
	s_nop 0
	global_load_lds_dwordx4 v[210:211], off
	s_waitcnt vmcnt(8)
	s_waitcnt lgkmcnt(0)
	s_setprio 1
	s_barrier

	v_mfma_f32_16x16x32_bf16 v[62:65], v[90:93], v[162:165], v[62:65]
	v_mfma_f32_16x16x32_bf16 v[58:61], v[114:117], v[162:165], v[58:61]
	v_mfma_f32_16x16x32_bf16 v[46:49], v[90:93], v[170:173], v[46:49]
	v_mfma_f32_16x16x32_bf16 v[42:45], v[114:117], v[170:173], v[42:45]
	v_mfma_f32_16x16x32_bf16 v[30:33], v[90:93], v[178:181], v[30:33]
	v_mfma_f32_16x16x32_bf16 v[26:29], v[114:117], v[178:181], v[26:29]
	v_mfma_f32_16x16x32_bf16 v[14:17], v[90:93], v[202:205], v[14:17]
	v_mfma_f32_16x16x32_bf16 v[10:13], v[114:117], v[202:205], v[10:13]
	v_mfma_f32_16x16x32_bf16 v[62:65], v[102:105], v[166:169], v[62:65]
	v_mfma_f32_16x16x32_bf16 v[58:61], v[126:129], v[166:169], v[58:61]
	v_mfma_f32_16x16x32_bf16 v[46:49], v[102:105], v[174:177], v[46:49]
	v_mfma_f32_16x16x32_bf16 v[42:45], v[126:129], v[174:177], v[42:45]
	v_mfma_f32_16x16x32_bf16 v[30:33], v[102:105], v[182:185], v[30:33]
	v_mfma_f32_16x16x32_bf16 v[26:29], v[126:129], v[182:185], v[26:29]
	v_mfma_f32_16x16x32_bf16 v[14:17], v[102:105], v[206:209], v[14:17]
	v_mfma_f32_16x16x32_bf16 v[10:13], v[126:129], v[206:209], v[10:13]
	s_setprio 0
	s_setprio 1
	v_mfma_f32_16x16x32_bf16 v[54:57], v[138:141], v[162:165], v[54:57]
	v_mfma_f32_16x16x32_bf16 v[50:53], v[154:157], v[162:165], v[50:53]
	v_mfma_f32_16x16x32_bf16 v[38:41], v[138:141], v[170:173], v[38:41]
	v_mfma_f32_16x16x32_bf16 v[34:37], v[154:157], v[170:173], v[34:37]
	v_mfma_f32_16x16x32_bf16 v[22:25], v[138:141], v[178:181], v[22:25]
	v_mfma_f32_16x16x32_bf16 v[18:21], v[154:157], v[178:181], v[18:21]
	v_mfma_f32_16x16x32_bf16 v[6:9], v[138:141], v[202:205], v[6:9]
	v_mfma_f32_16x16x32_bf16 v[2:5], v[154:157], v[202:205], v[2:5]
	v_mfma_f32_16x16x32_bf16 v[54:57], v[142:145], v[166:169], v[54:57]
	v_mfma_f32_16x16x32_bf16 v[50:53], v[158:161], v[166:169], v[50:53]
	v_mfma_f32_16x16x32_bf16 v[38:41], v[142:145], v[174:177], v[38:41]
	v_mfma_f32_16x16x32_bf16 v[34:37], v[158:161], v[174:177], v[34:37]
	v_mfma_f32_16x16x32_bf16 v[22:25], v[142:145], v[182:185], v[22:25]
	v_mfma_f32_16x16x32_bf16 v[18:21], v[158:161], v[182:185], v[18:21]
	v_mfma_f32_16x16x32_bf16 v[6:9], v[142:145], v[206:209], v[6:9]
	v_mfma_f32_16x16x32_bf16 v[2:5], v[158:161], v[206:209], v[2:5]
	s_setprio 0
	s_barrier
	s_add_i32 s51, s51, 2
	s_add_u32 s49, s49, 0x100
	s_addc_u32 s50, s50, 0
	s_cmpk_gt_u32 s51, 0x55
	s_mov_b64 s[20:21], s[22:23]
	s_cbranch_scc0 .LBB0_243
	s_and_b64 vcc, exec, s[16:17]
	s_cbranch_vccz .LBB0_246
	s_barrier

.LBB0_443:
	s_add_u32 s0, s26, 0xfff80080
	s_addc_u32 s1, s27, -1
	s_add_i32 s56, 0, 0x10000
	s_cmp_eq_u32 s55, 28
	s_cselect_b32 s31, s19, s1
	s_cselect_b32 s30, s51, s0
	v_add_u32_e32 v140, s56, v144
	s_cselect_b32 s29, s17, s54
	s_cselect_b32 s28, s52, s53
	s_add_i32 s0, 0, 0x14000
	ds_read_b128 v[146:149], v140
	ds_read_b128 v[150:153], v140 offset:1024
	ds_read_b128 v[154:157], v140 offset:2048
	ds_read_b128 v[158:161], v140 offset:3072
	v_add_u32_e32 v140, s0, v144
	ds_read_b128 v[162:165], v140
	ds_read_b128 v[166:169], v140 offset:1024
	ds_read_b128 v[170:173], v140 offset:2048
	ds_read_b128 v[174:177], v140 offset:3072
	v_lshl_add_u64 v[140:141], s[26:27], 0, v[136:137]
	s_add_i32 m0, s25, 0xc000
	ds_read_b128 v[178:181], v145
	ds_read_b128 v[182:185], v145 offset:1024
	ds_read_b128 v[192:195], v145 offset:2048
	ds_read_b128 v[196:199], v145 offset:3072
	ds_read_b128 v[200:203], v145 offset:4096
	ds_read_b128 v[204:207], v145 offset:5120
	ds_read_b128 v[208:211], v145 offset:6144
	ds_read_b128 v[212:215], v145 offset:7168
	global_load_lds_dwordx4 v[140:141], off
	v_lshl_add_u64 v[140:141], s[26:27], 0, v[138:139]
	s_add_i32 m0, s25, 0xe000
	s_nop 0
	global_load_lds_dwordx4 v[140:141], off
	s_waitcnt vmcnt(8)
	s_waitcnt lgkmcnt(0)
	s_setprio 1
	s_barrier

	v_mfma_f32_16x16x32_bf16 v[126:129], v[146:149], v[178:181], v[126:129]
	v_mfma_f32_16x16x32_bf16 v[122:125], v[154:157], v[178:181], v[122:125]
	v_mfma_f32_16x16x32_bf16 v[114:117], v[146:149], v[192:195], v[114:117]
	v_mfma_f32_16x16x32_bf16 v[106:109], v[154:157], v[192:195], v[106:109]
	v_mfma_f32_16x16x32_bf16 v[98:101], v[146:149], v[200:203], v[98:101]
	v_mfma_f32_16x16x32_bf16 v[90:93], v[154:157], v[200:203], v[90:93]
	v_mfma_f32_16x16x32_bf16 v[82:85], v[146:149], v[208:211], v[82:85]
	v_mfma_f32_16x16x32_bf16 v[74:77], v[154:157], v[208:211], v[74:77]
	v_mfma_f32_16x16x32_bf16 v[126:129], v[150:153], v[182:185], v[126:129]
	v_mfma_f32_16x16x32_bf16 v[122:125], v[158:161], v[182:185], v[122:125]
	v_mfma_f32_16x16x32_bf16 v[114:117], v[150:153], v[196:199], v[114:117]
	v_mfma_f32_16x16x32_bf16 v[106:109], v[158:161], v[196:199], v[106:109]
	v_mfma_f32_16x16x32_bf16 v[98:101], v[150:153], v[204:207], v[98:101]
	v_mfma_f32_16x16x32_bf16 v[90:93], v[158:161], v[204:207], v[90:93]
	v_mfma_f32_16x16x32_bf16 v[82:85], v[150:153], v[212:215], v[82:85]
	v_mfma_f32_16x16x32_bf16 v[74:77], v[158:161], v[212:215], v[74:77]
	s_setprio 0
	s_setprio 1
	v_mfma_f32_16x16x32_bf16 v[118:121], v[162:165], v[178:181], v[118:121]
	v_mfma_f32_16x16x32_bf16 v[110:113], v[170:173], v[178:181], v[110:113]
	v_mfma_f32_16x16x32_bf16 v[102:105], v[162:165], v[192:195], v[102:105]
	v_mfma_f32_16x16x32_bf16 v[94:97], v[170:173], v[192:195], v[94:97]
	v_mfma_f32_16x16x32_bf16 v[86:89], v[162:165], v[200:203], v[86:89]
	v_mfma_f32_16x16x32_bf16 v[78:81], v[170:173], v[200:203], v[78:81]
	v_mfma_f32_16x16x32_bf16 v[70:73], v[162:165], v[208:211], v[70:73]
	v_mfma_f32_16x16x32_bf16 v[66:69], v[170:173], v[208:211], v[66:69]
	v_mfma_f32_16x16x32_bf16 v[118:121], v[166:169], v[182:185], v[118:121]
	v_mfma_f32_16x16x32_bf16 v[110:113], v[174:177], v[182:185], v[110:113]
	v_mfma_f32_16x16x32_bf16 v[102:105], v[166:169], v[196:199], v[102:105]
	v_mfma_f32_16x16x32_bf16 v[94:97], v[174:177], v[196:199], v[94:97]
	v_mfma_f32_16x16x32_bf16 v[86:89], v[166:169], v[204:207], v[86:89]
	v_mfma_f32_16x16x32_bf16 v[78:81], v[174:177], v[204:207], v[78:81]
	v_mfma_f32_16x16x32_bf16 v[70:73], v[166:169], v[212:215], v[70:73]
	v_mfma_f32_16x16x32_bf16 v[66:69], v[174:177], v[212:215], v[66:69]
	s_setprio 0
	s_barrier
	s_add_i32 s1, s56, s39
	v_lshl_add_u64 v[140:141], s[28:29], 0, v[186:187]
	s_mov_b32 m0, s1
	ds_read_b128 v[178:181], v145 offset:16384
	ds_read_b128 v[182:185], v145 offset:17408
	ds_read_b128 v[192:195], v145 offset:18432
	ds_read_b128 v[196:199], v145 offset:19456
	ds_read_b128 v[200:203], v145 offset:20480
	ds_read_b128 v[204:207], v145 offset:21504
	ds_read_b128 v[208:211], v145 offset:22528
	ds_read_b128 v[212:215], v145 offset:23552
	global_load_lds_dwordx4 v[140:141], off
	s_add_i32 m0, s1, 0x2000
	s_add_u32 s56, s28, 0x80000
	v_lshl_add_u64 v[188:189], s[28:29], 0, v[130:131]
	s_addc_u32 s57, s29, 0
	s_add_i32 s0, s0, s39
	global_load_lds_dwordx4 v[188:189], off
	v_lshl_add_u64 v[216:217], s[56:57], 0, v[186:187]
	s_mov_b32 m0, s0
	v_lshl_add_u64 v[218:219], s[30:31], 0, v[132:133]
	global_load_lds_dwordx4 v[216:217], off
	v_lshl_add_u64 v[216:217], s[56:57], 0, v[130:131]
	s_add_i32 m0, s0, 0x2000
	s_nop 0
	global_load_lds_dwordx4 v[216:217], off
	v_lshl_add_u64 v[216:217], s[30:31], 0, v[134:135]
	s_mov_b32 m0, s25
	s_nop 0
	global_load_lds_dwordx4 v[216:217], off
	s_mov_b32 m0, s40
	s_nop 0
	global_load_lds_dwordx4 v[218:219], off
	s_waitcnt vmcnt(8)
	s_waitcnt lgkmcnt(0)
	s_setprio 1
	s_barrier

	v_mfma_f32_16x16x32_bf16 v[62:65], v[146:149], v[178:181], v[62:65]
	v_mfma_f32_16x16x32_bf16 v[58:61], v[154:157], v[178:181], v[58:61]
	v_mfma_f32_16x16x32_bf16 v[50:53], v[146:149], v[192:195], v[50:53]
	v_mfma_f32_16x16x32_bf16 v[42:45], v[154:157], v[192:195], v[42:45]
	v_mfma_f32_16x16x32_bf16 v[34:37], v[146:149], v[200:203], v[34:37]
	v_mfma_f32_16x16x32_bf16 v[26:29], v[154:157], v[200:203], v[26:29]
	v_mfma_f32_16x16x32_bf16 v[18:21], v[146:149], v[208:211], v[18:21]
	v_mfma_f32_16x16x32_bf16 v[10:13], v[154:157], v[208:211], v[10:13]
	v_mfma_f32_16x16x32_bf16 v[62:65], v[150:153], v[182:185], v[62:65]
	v_mfma_f32_16x16x32_bf16 v[58:61], v[158:161], v[182:185], v[58:61]
	v_mfma_f32_16x16x32_bf16 v[50:53], v[150:153], v[196:199], v[50:53]
	v_mfma_f32_16x16x32_bf16 v[42:45], v[158:161], v[196:199], v[42:45]
	v_mfma_f32_16x16x32_bf16 v[34:37], v[150:153], v[204:207], v[34:37]
	v_mfma_f32_16x16x32_bf16 v[26:29], v[158:161], v[204:207], v[26:29]
	v_mfma_f32_16x16x32_bf16 v[18:21], v[150:153], v[212:215], v[18:21]
	v_mfma_f32_16x16x32_bf16 v[10:13], v[158:161], v[212:215], v[10:13]
	s_setprio 0
	s_setprio 1
	v_mfma_f32_16x16x32_bf16 v[54:57], v[162:165], v[178:181], v[54:57]
	v_mfma_f32_16x16x32_bf16 v[46:49], v[170:173], v[178:181], v[46:49]
	v_mfma_f32_16x16x32_bf16 v[38:41], v[162:165], v[192:195], v[38:41]
	v_mfma_f32_16x16x32_bf16 v[30:33], v[170:173], v[192:195], v[30:33]
	v_mfma_f32_16x16x32_bf16 v[22:25], v[162:165], v[200:203], v[22:25]
	v_mfma_f32_16x16x32_bf16 v[14:17], v[170:173], v[200:203], v[14:17]
	v_mfma_f32_16x16x32_bf16 v[6:9], v[162:165], v[208:211], v[6:9]
	v_mfma_f32_16x16x32_bf16 v[2:5], v[170:173], v[208:211], v[2:5]
	v_mfma_f32_16x16x32_bf16 v[54:57], v[166:169], v[182:185], v[54:57]
	v_mfma_f32_16x16x32_bf16 v[46:49], v[174:177], v[182:185], v[46:49]
	v_mfma_f32_16x16x32_bf16 v[38:41], v[166:169], v[196:199], v[38:41]
	v_mfma_f32_16x16x32_bf16 v[30:33], v[174:177], v[196:199], v[30:33]
	v_mfma_f32_16x16x32_bf16 v[22:25], v[166:169], v[204:207], v[22:25]
	v_mfma_f32_16x16x32_bf16 v[14:17], v[174:177], v[204:207], v[14:17]
	v_mfma_f32_16x16x32_bf16 v[6:9], v[166:169], v[212:215], v[6:9]
	v_mfma_f32_16x16x32_bf16 v[2:5], v[174:177], v[212:215], v[2:5]
	s_setprio 0
	s_barrier
	s_add_i32 s0, 0, 0x18000
	s_add_i32 s1, 0, 0x1c000
	v_add_u32_e32 v158, s0, v144
	v_add_u32_e32 v174, s1, v144
	ds_read_b128 v[146:149], v158
	ds_read_b128 v[150:153], v158 offset:1024
	ds_read_b128 v[154:157], v158 offset:2048
	ds_read_b128 v[158:161], v158 offset:3072
	ds_read_b128 v[162:165], v174
	ds_read_b128 v[166:169], v174 offset:1024
	ds_read_b128 v[170:173], v174 offset:2048
	ds_read_b128 v[174:177], v174 offset:3072
	s_add_u32 s30, s30, 0x80000
	s_addc_u32 s31, s31, 0
	s_mov_b32 m0, s41
	v_lshl_add_u64 v[220:221], s[30:31], 0, v[134:135]
	ds_read_b128 v[178:181], v145 offset:32768
	ds_read_b128 v[182:185], v145 offset:33792
	ds_read_b128 v[192:195], v145 offset:34816
	ds_read_b128 v[196:199], v145 offset:35840
	ds_read_b128 v[200:203], v145 offset:36864
	ds_read_b128 v[204:207], v145 offset:37888
	ds_read_b128 v[208:211], v145 offset:38912
	ds_read_b128 v[212:215], v145 offset:39936
	global_load_lds_dwordx4 v[220:221], off
	v_lshl_add_u64 v[220:221], s[30:31], 0, v[132:133]
	s_mov_b32 m0, s42
	s_nop 0
	global_load_lds_dwordx4 v[220:221], off
	s_waitcnt vmcnt(8)
	s_waitcnt lgkmcnt(0)
	s_setprio 1
	s_barrier

	v_mfma_f32_16x16x32_bf16 v[126:129], v[146:149], v[178:181], v[126:129]
	v_mfma_f32_16x16x32_bf16 v[122:125], v[154:157], v[178:181], v[122:125]
	v_mfma_f32_16x16x32_bf16 v[114:117], v[146:149], v[192:195], v[114:117]
	v_mfma_f32_16x16x32_bf16 v[106:109], v[154:157], v[192:195], v[106:109]
	v_mfma_f32_16x16x32_bf16 v[98:101], v[146:149], v[200:203], v[98:101]
	v_mfma_f32_16x16x32_bf16 v[90:93], v[154:157], v[200:203], v[90:93]
	v_mfma_f32_16x16x32_bf16 v[82:85], v[146:149], v[208:211], v[82:85]
	v_mfma_f32_16x16x32_bf16 v[74:77], v[154:157], v[208:211], v[74:77]
	v_mfma_f32_16x16x32_bf16 v[126:129], v[150:153], v[182:185], v[126:129]
	v_mfma_f32_16x16x32_bf16 v[122:125], v[158:161], v[182:185], v[122:125]
	v_mfma_f32_16x16x32_bf16 v[114:117], v[150:153], v[196:199], v[114:117]
	v_mfma_f32_16x16x32_bf16 v[106:109], v[158:161], v[196:199], v[106:109]
	v_mfma_f32_16x16x32_bf16 v[98:101], v[150:153], v[204:207], v[98:101]
	v_mfma_f32_16x16x32_bf16 v[90:93], v[158:161], v[204:207], v[90:93]
	v_mfma_f32_16x16x32_bf16 v[82:85], v[150:153], v[212:215], v[82:85]
	v_mfma_f32_16x16x32_bf16 v[74:77], v[158:161], v[212:215], v[74:77]
	s_setprio 0
	s_setprio 1
	v_mfma_f32_16x16x32_bf16 v[118:121], v[162:165], v[178:181], v[118:121]
	v_mfma_f32_16x16x32_bf16 v[110:113], v[170:173], v[178:181], v[110:113]
	v_mfma_f32_16x16x32_bf16 v[102:105], v[162:165], v[192:195], v[102:105]
	v_mfma_f32_16x16x32_bf16 v[94:97], v[170:173], v[192:195], v[94:97]
	v_mfma_f32_16x16x32_bf16 v[86:89], v[162:165], v[200:203], v[86:89]
	v_mfma_f32_16x16x32_bf16 v[78:81], v[170:173], v[200:203], v[78:81]
	v_mfma_f32_16x16x32_bf16 v[70:73], v[162:165], v[208:211], v[70:73]
	v_mfma_f32_16x16x32_bf16 v[66:69], v[170:173], v[208:211], v[66:69]
	v_mfma_f32_16x16x32_bf16 v[118:121], v[166:169], v[182:185], v[118:121]
	v_mfma_f32_16x16x32_bf16 v[110:113], v[174:177], v[182:185], v[110:113]
	v_mfma_f32_16x16x32_bf16 v[102:105], v[166:169], v[196:199], v[102:105]
	v_mfma_f32_16x16x32_bf16 v[94:97], v[174:177], v[196:199], v[94:97]
	v_mfma_f32_16x16x32_bf16 v[86:89], v[166:169], v[204:207], v[86:89]
	v_mfma_f32_16x16x32_bf16 v[78:81], v[174:177], v[204:207], v[78:81]
	v_mfma_f32_16x16x32_bf16 v[70:73], v[166:169], v[212:215], v[70:73]
	v_mfma_f32_16x16x32_bf16 v[66:69], v[174:177], v[212:215], v[66:69]
	s_setprio 0
	s_barrier
	s_add_i32 s0, s0, s39
	v_lshl_add_u64 v[140:141], v[140:141], 0, s[84:85]
	s_mov_b32 m0, s0
	ds_read_b128 v[178:181], v145 offset:49152
	ds_read_b128 v[182:185], v145 offset:50176
	ds_read_b128 v[192:195], v145 offset:51200
	ds_read_b128 v[196:199], v145 offset:52224
	ds_read_b128 v[200:203], v145 offset:53248
	ds_read_b128 v[204:207], v145 offset:54272
	ds_read_b128 v[208:211], v145 offset:55296
	ds_read_b128 v[212:215], v145 offset:56320
	global_load_lds_dwordx4 v[140:141], off
	s_add_i32 m0, s0, 0x2000
	s_add_u32 s28, s28, 0x80080
	v_lshl_add_u64 v[140:141], v[188:189], 0, s[84:85]
	s_addc_u32 s29, s29, 0
	s_add_i32 s0, s1, s39
	global_load_lds_dwordx4 v[140:141], off
	v_lshl_add_u64 v[140:141], s[28:29], 0, v[186:187]
	s_mov_b32 m0, s0
	s_nop 0
	global_load_lds_dwordx4 v[140:141], off
	v_lshl_add_u64 v[140:141], s[28:29], 0, v[130:131]
	s_add_i32 m0, s0, 0x2000
	s_nop 0
	global_load_lds_dwordx4 v[140:141], off
	v_lshl_add_u64 v[140:141], v[216:217], 0, s[84:85]
	s_mov_b32 m0, s43
	s_nop 0
	global_load_lds_dwordx4 v[140:141], off
	v_lshl_add_u64 v[140:141], v[218:219], 0, s[84:85]
	s_mov_b32 m0, s44
	s_nop 0
	global_load_lds_dwordx4 v[140:141], off
	s_waitcnt vmcnt(8)
	s_waitcnt lgkmcnt(0)
	s_setprio 1
	s_barrier

	v_mfma_f32_16x16x32_bf16 v[62:65], v[146:149], v[178:181], v[62:65]
	v_mfma_f32_16x16x32_bf16 v[58:61], v[154:157], v[178:181], v[58:61]
	v_mfma_f32_16x16x32_bf16 v[50:53], v[146:149], v[192:195], v[50:53]
	v_mfma_f32_16x16x32_bf16 v[42:45], v[154:157], v[192:195], v[42:45]
	v_mfma_f32_16x16x32_bf16 v[34:37], v[146:149], v[200:203], v[34:37]
	v_mfma_f32_16x16x32_bf16 v[26:29], v[154:157], v[200:203], v[26:29]
	v_mfma_f32_16x16x32_bf16 v[18:21], v[146:149], v[208:211], v[18:21]
	v_mfma_f32_16x16x32_bf16 v[10:13], v[154:157], v[208:211], v[10:13]
	v_mfma_f32_16x16x32_bf16 v[62:65], v[150:153], v[182:185], v[62:65]
	v_mfma_f32_16x16x32_bf16 v[58:61], v[158:161], v[182:185], v[58:61]
	v_mfma_f32_16x16x32_bf16 v[50:53], v[150:153], v[196:199], v[50:53]
	v_mfma_f32_16x16x32_bf16 v[42:45], v[158:161], v[196:199], v[42:45]
	v_mfma_f32_16x16x32_bf16 v[34:37], v[150:153], v[204:207], v[34:37]
	v_mfma_f32_16x16x32_bf16 v[26:29], v[158:161], v[204:207], v[26:29]
	v_mfma_f32_16x16x32_bf16 v[18:21], v[150:153], v[212:215], v[18:21]
	v_mfma_f32_16x16x32_bf16 v[10:13], v[158:161], v[212:215], v[10:13]
	s_setprio 0
	s_setprio 1
	v_mfma_f32_16x16x32_bf16 v[54:57], v[162:165], v[178:181], v[54:57]
	v_mfma_f32_16x16x32_bf16 v[46:49], v[170:173], v[178:181], v[46:49]
	v_mfma_f32_16x16x32_bf16 v[38:41], v[162:165], v[192:195], v[38:41]
	v_mfma_f32_16x16x32_bf16 v[30:33], v[170:173], v[192:195], v[30:33]
	v_mfma_f32_16x16x32_bf16 v[22:25], v[162:165], v[200:203], v[22:25]
	v_mfma_f32_16x16x32_bf16 v[14:17], v[170:173], v[200:203], v[14:17]
	v_mfma_f32_16x16x32_bf16 v[6:9], v[162:165], v[208:211], v[6:9]
	v_mfma_f32_16x16x32_bf16 v[2:5], v[170:173], v[208:211], v[2:5]
	v_mfma_f32_16x16x32_bf16 v[54:57], v[166:169], v[182:185], v[54:57]
	v_mfma_f32_16x16x32_bf16 v[46:49], v[174:177], v[182:185], v[46:49]
	v_mfma_f32_16x16x32_bf16 v[38:41], v[166:169], v[196:199], v[38:41]
	v_mfma_f32_16x16x32_bf16 v[30:33], v[174:177], v[196:199], v[30:33]
	v_mfma_f32_16x16x32_bf16 v[22:25], v[166:169], v[204:207], v[22:25]
	v_mfma_f32_16x16x32_bf16 v[14:17], v[174:177], v[204:207], v[14:17]
	v_mfma_f32_16x16x32_bf16 v[6:9], v[166:169], v[212:215], v[6:9]
	v_mfma_f32_16x16x32_bf16 v[2:5], v[174:177], v[212:215], v[2:5]
	s_setprio 0
	s_barrier
	s_add_i32 s55, s55, 2
	s_add_u32 s26, s26, 0x100
	s_addc_u32 s27, s27, 0
	s_add_u32 s53, s53, 0x100
	s_addc_u32 s54, s54, 0
	s_cmp_gt_u32 s55, 29
	s_cbranch_scc0 .LBB0_443
	s_and_b64 vcc, exec, s[14:15]
	s_cbranch_vccz .LBB0_446
	s_barrier

.LBB0_1126:
	s_add_u32 s0, s28, 0xfff80080
	s_addc_u32 s1, s29, -1
	s_add_i32 s54, 0, 0x10000
	s_cmp_eq_u32 s53, 28
	s_cselect_b32 s35, s19, s1
	s_cselect_b32 s34, s25, s0
	s_cselect_b32 s31, s17, s52
	s_cselect_b32 s30, s27, s51
	s_add_i32 s55, 0, 0x14000
	v_add_u32_e32 v126, s54, v237
	v_add_u32_e32 v158, s55, v237
	ds_read_b128 v[90:93], v126
	ds_read_b128 v[102:105], v126 offset:1024
	ds_read_b128 v[114:117], v126 offset:2048
	ds_read_b128 v[126:129], v126 offset:3072
	ds_read_b128 v[138:141], v158
	ds_read_b128 v[142:145], v158 offset:1024
	ds_read_b128 v[154:157], v158 offset:2048
	ds_read_b128 v[158:161], v158 offset:3072
	v_lshl_add_u64 v[188:189], s[28:29], 0, v[198:199]
	s_add_i32 m0, s40, 0xc000
	ds_read_b128 v[162:165], v238
	ds_read_b128 v[166:169], v238 offset:1024
	ds_read_b128 v[170:173], v238 offset:2048
	ds_read_b128 v[174:177], v238 offset:3072
	ds_read_b128 v[178:181], v238 offset:4096
	ds_read_b128 v[182:185], v238 offset:5120
	ds_read_b128 v[202:205], v238 offset:6144
	ds_read_b128 v[206:209], v238 offset:7168
	global_load_lds_dwordx4 v[188:189], off
	v_lshl_add_u64 v[188:189], s[28:29], 0, v[200:201]
	s_add_i32 m0, s40, 0xe000
	s_nop 0
	global_load_lds_dwordx4 v[188:189], off
	s_waitcnt vmcnt(8)
	s_waitcnt lgkmcnt(0)
	s_setprio 1
	s_barrier

	v_mfma_f32_16x16x32_bf16 v[150:153], v[90:93], v[162:165], v[150:153]
	v_mfma_f32_16x16x32_bf16 v[146:149], v[114:117], v[162:165], v[146:149]
	v_mfma_f32_16x16x32_bf16 v[122:125], v[90:93], v[170:173], v[122:125]
	v_mfma_f32_16x16x32_bf16 v[118:121], v[114:117], v[170:173], v[118:121]
	v_mfma_f32_16x16x32_bf16 v[98:101], v[90:93], v[178:181], v[98:101]
	v_mfma_f32_16x16x32_bf16 v[94:97], v[114:117], v[178:181], v[94:97]
	v_mfma_f32_16x16x32_bf16 v[78:81], v[90:93], v[202:205], v[78:81]
	v_mfma_f32_16x16x32_bf16 v[74:77], v[114:117], v[202:205], v[74:77]
	v_mfma_f32_16x16x32_bf16 v[150:153], v[102:105], v[166:169], v[150:153]
	v_mfma_f32_16x16x32_bf16 v[146:149], v[126:129], v[166:169], v[146:149]
	v_mfma_f32_16x16x32_bf16 v[122:125], v[102:105], v[174:177], v[122:125]
	v_mfma_f32_16x16x32_bf16 v[118:121], v[126:129], v[174:177], v[118:121]
	v_mfma_f32_16x16x32_bf16 v[98:101], v[102:105], v[182:185], v[98:101]
	v_mfma_f32_16x16x32_bf16 v[94:97], v[126:129], v[182:185], v[94:97]
	v_mfma_f32_16x16x32_bf16 v[78:81], v[102:105], v[206:209], v[78:81]
	v_mfma_f32_16x16x32_bf16 v[74:77], v[126:129], v[206:209], v[74:77]
	s_setprio 0
	s_setprio 1
	v_mfma_f32_16x16x32_bf16 v[134:137], v[138:141], v[162:165], v[134:137]
	v_mfma_f32_16x16x32_bf16 v[130:133], v[154:157], v[162:165], v[130:133]
	v_mfma_f32_16x16x32_bf16 v[110:113], v[138:141], v[170:173], v[110:113]
	v_mfma_f32_16x16x32_bf16 v[106:109], v[154:157], v[170:173], v[106:109]
	v_mfma_f32_16x16x32_bf16 v[86:89], v[138:141], v[178:181], v[86:89]
	v_mfma_f32_16x16x32_bf16 v[82:85], v[154:157], v[178:181], v[82:85]
	v_mfma_f32_16x16x32_bf16 v[70:73], v[138:141], v[202:205], v[70:73]
	v_mfma_f32_16x16x32_bf16 v[66:69], v[154:157], v[202:205], v[66:69]
	v_mfma_f32_16x16x32_bf16 v[134:137], v[142:145], v[166:169], v[134:137]
	v_mfma_f32_16x16x32_bf16 v[130:133], v[158:161], v[166:169], v[130:133]
	v_mfma_f32_16x16x32_bf16 v[110:113], v[142:145], v[174:177], v[110:113]
	v_mfma_f32_16x16x32_bf16 v[106:109], v[158:161], v[174:177], v[106:109]
	v_mfma_f32_16x16x32_bf16 v[86:89], v[142:145], v[182:185], v[86:89]
	v_mfma_f32_16x16x32_bf16 v[82:85], v[158:161], v[182:185], v[82:85]
	v_mfma_f32_16x16x32_bf16 v[70:73], v[142:145], v[206:209], v[70:73]
	v_mfma_f32_16x16x32_bf16 v[66:69], v[158:161], v[206:209], v[66:69]
	s_setprio 0
	s_barrier
	s_add_i32 s0, s54, s39
	v_lshl_add_u64 v[188:189], s[30:31], 0, v[186:187]
	s_mov_b32 m0, s0
	ds_read_b128 v[162:165], v238 offset:16384
	ds_read_b128 v[166:169], v238 offset:17408
	ds_read_b128 v[170:173], v238 offset:18432
	ds_read_b128 v[174:177], v238 offset:19456
	ds_read_b128 v[178:181], v238 offset:20480
	ds_read_b128 v[182:185], v238 offset:21504
	ds_read_b128 v[202:205], v238 offset:22528
	ds_read_b128 v[206:209], v238 offset:23552
	global_load_lds_dwordx4 v[188:189], off
	s_add_i32 m0, s0, 0x2000
	s_add_u32 s0, s30, 0x80000
	v_lshl_add_u64 v[210:211], s[30:31], 0, v[196:197]
	s_addc_u32 s1, s31, 0
	s_add_i32 s54, s55, s39
	global_load_lds_dwordx4 v[210:211], off
	v_lshl_add_u64 v[212:213], s[0:1], 0, v[186:187]
	s_mov_b32 m0, s54
	v_lshl_add_u64 v[214:215], s[34:35], 0, v[194:195]
	global_load_lds_dwordx4 v[212:213], off
	v_lshl_add_u64 v[212:213], s[0:1], 0, v[196:197]
	s_add_i32 m0, s54, 0x2000
	s_nop 0
	global_load_lds_dwordx4 v[212:213], off
	v_lshl_add_u64 v[212:213], s[34:35], 0, v[192:193]
	s_mov_b32 m0, s40
	s_nop 0
	global_load_lds_dwordx4 v[212:213], off
	s_mov_b32 m0, s41
	s_nop 0
	global_load_lds_dwordx4 v[214:215], off
	s_waitcnt vmcnt(8)
	s_waitcnt lgkmcnt(0)
	s_setprio 1
	s_barrier

	v_mfma_f32_16x16x32_bf16 v[62:65], v[90:93], v[162:165], v[62:65]
	v_mfma_f32_16x16x32_bf16 v[58:61], v[114:117], v[162:165], v[58:61]
	v_mfma_f32_16x16x32_bf16 v[46:49], v[90:93], v[170:173], v[46:49]
	v_mfma_f32_16x16x32_bf16 v[42:45], v[114:117], v[170:173], v[42:45]
	v_mfma_f32_16x16x32_bf16 v[30:33], v[90:93], v[178:181], v[30:33]
	v_mfma_f32_16x16x32_bf16 v[26:29], v[114:117], v[178:181], v[26:29]
	v_mfma_f32_16x16x32_bf16 v[14:17], v[90:93], v[202:205], v[14:17]
	v_mfma_f32_16x16x32_bf16 v[10:13], v[114:117], v[202:205], v[10:13]
	v_mfma_f32_16x16x32_bf16 v[62:65], v[102:105], v[166:169], v[62:65]
	v_mfma_f32_16x16x32_bf16 v[58:61], v[126:129], v[166:169], v[58:61]
	v_mfma_f32_16x16x32_bf16 v[46:49], v[102:105], v[174:177], v[46:49]
	v_mfma_f32_16x16x32_bf16 v[42:45], v[126:129], v[174:177], v[42:45]
	v_mfma_f32_16x16x32_bf16 v[30:33], v[102:105], v[182:185], v[30:33]
	v_mfma_f32_16x16x32_bf16 v[26:29], v[126:129], v[182:185], v[26:29]
	v_mfma_f32_16x16x32_bf16 v[14:17], v[102:105], v[206:209], v[14:17]
	v_mfma_f32_16x16x32_bf16 v[10:13], v[126:129], v[206:209], v[10:13]
	s_setprio 0
	s_setprio 1
	v_mfma_f32_16x16x32_bf16 v[54:57], v[138:141], v[162:165], v[54:57]
	v_mfma_f32_16x16x32_bf16 v[50:53], v[154:157], v[162:165], v[50:53]
	v_mfma_f32_16x16x32_bf16 v[38:41], v[138:141], v[170:173], v[38:41]
	v_mfma_f32_16x16x32_bf16 v[34:37], v[154:157], v[170:173], v[34:37]
	v_mfma_f32_16x16x32_bf16 v[22:25], v[138:141], v[178:181], v[22:25]
	v_mfma_f32_16x16x32_bf16 v[18:21], v[154:157], v[178:181], v[18:21]
	v_mfma_f32_16x16x32_bf16 v[6:9], v[138:141], v[202:205], v[6:9]
	v_mfma_f32_16x16x32_bf16 v[2:5], v[154:157], v[202:205], v[2:5]
	v_mfma_f32_16x16x32_bf16 v[54:57], v[142:145], v[166:169], v[54:57]
	v_mfma_f32_16x16x32_bf16 v[50:53], v[158:161], v[166:169], v[50:53]
	v_mfma_f32_16x16x32_bf16 v[38:41], v[142:145], v[174:177], v[38:41]
	v_mfma_f32_16x16x32_bf16 v[34:37], v[158:161], v[174:177], v[34:37]
	v_mfma_f32_16x16x32_bf16 v[22:25], v[142:145], v[182:185], v[22:25]
	v_mfma_f32_16x16x32_bf16 v[18:21], v[158:161], v[182:185], v[18:21]
	v_mfma_f32_16x16x32_bf16 v[6:9], v[142:145], v[206:209], v[6:9]
	v_mfma_f32_16x16x32_bf16 v[2:5], v[158:161], v[206:209], v[2:5]
	s_setprio 0
	s_barrier
	s_add_i32 s54, 0, 0x18000
	s_add_i32 s55, 0, 0x1c000
	v_add_u32_e32 v126, s54, v237
	v_add_u32_e32 v158, s55, v237
	ds_read_b128 v[90:93], v126
	ds_read_b128 v[102:105], v126 offset:1024
	ds_read_b128 v[114:117], v126 offset:2048
	ds_read_b128 v[126:129], v126 offset:3072
	ds_read_b128 v[138:141], v158
	ds_read_b128 v[142:145], v158 offset:1024
	ds_read_b128 v[154:157], v158 offset:2048
	ds_read_b128 v[158:161], v158 offset:3072
	s_add_u32 s0, s34, 0x80000
	s_addc_u32 s1, s35, 0
	s_mov_b32 m0, s42
	v_lshl_add_u64 v[216:217], s[0:1], 0, v[192:193]
	ds_read_b128 v[162:165], v238 offset:32768
	ds_read_b128 v[166:169], v238 offset:33792
	ds_read_b128 v[170:173], v238 offset:34816
	ds_read_b128 v[174:177], v238 offset:35840
	ds_read_b128 v[178:181], v238 offset:36864
	ds_read_b128 v[182:185], v238 offset:37888
	ds_read_b128 v[202:205], v238 offset:38912
	ds_read_b128 v[206:209], v238 offset:39936
	global_load_lds_dwordx4 v[216:217], off
	v_lshl_add_u64 v[216:217], s[0:1], 0, v[194:195]
	s_mov_b32 m0, s43
	s_nop 0
	global_load_lds_dwordx4 v[216:217], off
	s_waitcnt vmcnt(8)
	s_waitcnt lgkmcnt(0)
	s_setprio 1
	s_barrier

	v_mfma_f32_16x16x32_bf16 v[150:153], v[90:93], v[162:165], v[150:153]
	v_mfma_f32_16x16x32_bf16 v[146:149], v[114:117], v[162:165], v[146:149]
	v_mfma_f32_16x16x32_bf16 v[122:125], v[90:93], v[170:173], v[122:125]
	v_mfma_f32_16x16x32_bf16 v[118:121], v[114:117], v[170:173], v[118:121]
	v_mfma_f32_16x16x32_bf16 v[98:101], v[90:93], v[178:181], v[98:101]
	v_mfma_f32_16x16x32_bf16 v[94:97], v[114:117], v[178:181], v[94:97]
	v_mfma_f32_16x16x32_bf16 v[78:81], v[90:93], v[202:205], v[78:81]
	v_mfma_f32_16x16x32_bf16 v[74:77], v[114:117], v[202:205], v[74:77]
	v_mfma_f32_16x16x32_bf16 v[150:153], v[102:105], v[166:169], v[150:153]
	v_mfma_f32_16x16x32_bf16 v[146:149], v[126:129], v[166:169], v[146:149]
	v_mfma_f32_16x16x32_bf16 v[122:125], v[102:105], v[174:177], v[122:125]
	v_mfma_f32_16x16x32_bf16 v[118:121], v[126:129], v[174:177], v[118:121]
	v_mfma_f32_16x16x32_bf16 v[98:101], v[102:105], v[182:185], v[98:101]
	v_mfma_f32_16x16x32_bf16 v[94:97], v[126:129], v[182:185], v[94:97]
	v_mfma_f32_16x16x32_bf16 v[78:81], v[102:105], v[206:209], v[78:81]
	v_mfma_f32_16x16x32_bf16 v[74:77], v[126:129], v[206:209], v[74:77]
	s_setprio 0
	s_setprio 1
	v_mfma_f32_16x16x32_bf16 v[134:137], v[138:141], v[162:165], v[134:137]
	v_mfma_f32_16x16x32_bf16 v[130:133], v[154:157], v[162:165], v[130:133]
	v_mfma_f32_16x16x32_bf16 v[110:113], v[138:141], v[170:173], v[110:113]
	v_mfma_f32_16x16x32_bf16 v[106:109], v[154:157], v[170:173], v[106:109]
	v_mfma_f32_16x16x32_bf16 v[86:89], v[138:141], v[178:181], v[86:89]
	v_mfma_f32_16x16x32_bf16 v[82:85], v[154:157], v[178:181], v[82:85]
	v_mfma_f32_16x16x32_bf16 v[70:73], v[138:141], v[202:205], v[70:73]
	v_mfma_f32_16x16x32_bf16 v[66:69], v[154:157], v[202:205], v[66:69]
	v_mfma_f32_16x16x32_bf16 v[134:137], v[142:145], v[166:169], v[134:137]
	v_mfma_f32_16x16x32_bf16 v[130:133], v[158:161], v[166:169], v[130:133]
	v_mfma_f32_16x16x32_bf16 v[110:113], v[142:145], v[174:177], v[110:113]
	v_mfma_f32_16x16x32_bf16 v[106:109], v[158:161], v[174:177], v[106:109]
	v_mfma_f32_16x16x32_bf16 v[86:89], v[142:145], v[182:185], v[86:89]
	v_mfma_f32_16x16x32_bf16 v[82:85], v[158:161], v[182:185], v[82:85]
	v_mfma_f32_16x16x32_bf16 v[70:73], v[142:145], v[206:209], v[70:73]
	v_mfma_f32_16x16x32_bf16 v[66:69], v[158:161], v[206:209], v[66:69]
	s_setprio 0
	s_barrier
	s_add_i32 s0, s54, s39
	v_lshl_add_u64 v[188:189], v[188:189], 0, s[84:85]
	s_mov_b32 m0, s0
	ds_read_b128 v[162:165], v238 offset:49152
	ds_read_b128 v[166:169], v238 offset:50176
	ds_read_b128 v[170:173], v238 offset:51200
	ds_read_b128 v[174:177], v238 offset:52224
	ds_read_b128 v[178:181], v238 offset:53248
	ds_read_b128 v[182:185], v238 offset:54272
	ds_read_b128 v[202:205], v238 offset:55296
	ds_read_b128 v[206:209], v238 offset:56320
	global_load_lds_dwordx4 v[188:189], off
	s_add_i32 m0, s0, 0x2000
	s_add_u32 s0, s30, 0x80080
	v_lshl_add_u64 v[188:189], v[210:211], 0, s[84:85]
	s_addc_u32 s1, s31, 0
	s_add_i32 s30, s55, s39
	global_load_lds_dwordx4 v[188:189], off
	v_lshl_add_u64 v[188:189], s[0:1], 0, v[186:187]
	s_mov_b32 m0, s30
	s_nop 0
	global_load_lds_dwordx4 v[188:189], off
	v_lshl_add_u64 v[188:189], s[0:1], 0, v[196:197]
	s_add_i32 m0, s30, 0x2000
	s_nop 0
	global_load_lds_dwordx4 v[188:189], off
	v_lshl_add_u64 v[188:189], v[212:213], 0, s[84:85]
	s_mov_b32 m0, s47
	s_nop 0
	global_load_lds_dwordx4 v[188:189], off
	v_lshl_add_u64 v[188:189], v[214:215], 0, s[84:85]
	s_mov_b32 m0, s48
	s_nop 0
	global_load_lds_dwordx4 v[188:189], off
	s_waitcnt vmcnt(8)
	s_waitcnt lgkmcnt(0)
	s_setprio 1
	s_barrier

	v_mfma_f32_16x16x32_bf16 v[62:65], v[90:93], v[162:165], v[62:65]
	v_mfma_f32_16x16x32_bf16 v[58:61], v[114:117], v[162:165], v[58:61]
	v_mfma_f32_16x16x32_bf16 v[46:49], v[90:93], v[170:173], v[46:49]
	v_mfma_f32_16x16x32_bf16 v[42:45], v[114:117], v[170:173], v[42:45]
	v_mfma_f32_16x16x32_bf16 v[30:33], v[90:93], v[178:181], v[30:33]
	v_mfma_f32_16x16x32_bf16 v[26:29], v[114:117], v[178:181], v[26:29]
	v_mfma_f32_16x16x32_bf16 v[14:17], v[90:93], v[202:205], v[14:17]
	v_mfma_f32_16x16x32_bf16 v[10:13], v[114:117], v[202:205], v[10:13]
	v_mfma_f32_16x16x32_bf16 v[62:65], v[102:105], v[166:169], v[62:65]
	v_mfma_f32_16x16x32_bf16 v[58:61], v[126:129], v[166:169], v[58:61]
	v_mfma_f32_16x16x32_bf16 v[46:49], v[102:105], v[174:177], v[46:49]
	v_mfma_f32_16x16x32_bf16 v[42:45], v[126:129], v[174:177], v[42:45]
	v_mfma_f32_16x16x32_bf16 v[30:33], v[102:105], v[182:185], v[30:33]
	v_mfma_f32_16x16x32_bf16 v[26:29], v[126:129], v[182:185], v[26:29]
	v_mfma_f32_16x16x32_bf16 v[14:17], v[102:105], v[206:209], v[14:17]
	v_mfma_f32_16x16x32_bf16 v[10:13], v[126:129], v[206:209], v[10:13]
	s_setprio 0
	s_setprio 1
	v_mfma_f32_16x16x32_bf16 v[54:57], v[138:141], v[162:165], v[54:57]
	v_mfma_f32_16x16x32_bf16 v[50:53], v[154:157], v[162:165], v[50:53]
	v_mfma_f32_16x16x32_bf16 v[38:41], v[138:141], v[170:173], v[38:41]
	v_mfma_f32_16x16x32_bf16 v[34:37], v[154:157], v[170:173], v[34:37]
	v_mfma_f32_16x16x32_bf16 v[22:25], v[138:141], v[178:181], v[22:25]
	v_mfma_f32_16x16x32_bf16 v[18:21], v[154:157], v[178:181], v[18:21]
	v_mfma_f32_16x16x32_bf16 v[6:9], v[138:141], v[202:205], v[6:9]
	v_mfma_f32_16x16x32_bf16 v[2:5], v[154:157], v[202:205], v[2:5]
	v_mfma_f32_16x16x32_bf16 v[54:57], v[142:145], v[166:169], v[54:57]
	v_mfma_f32_16x16x32_bf16 v[50:53], v[158:161], v[166:169], v[50:53]
	v_mfma_f32_16x16x32_bf16 v[38:41], v[142:145], v[174:177], v[38:41]
	v_mfma_f32_16x16x32_bf16 v[34:37], v[158:161], v[174:177], v[34:37]
	v_mfma_f32_16x16x32_bf16 v[22:25], v[142:145], v[182:185], v[22:25]
	v_mfma_f32_16x16x32_bf16 v[18:21], v[158:161], v[182:185], v[18:21]
	v_mfma_f32_16x16x32_bf16 v[6:9], v[142:145], v[206:209], v[6:9]
	v_mfma_f32_16x16x32_bf16 v[2:5], v[158:161], v[206:209], v[2:5]
	s_setprio 0
	s_barrier
	s_add_i32 s53, s53, 2
	s_add_u32 s28, s28, 0x100
	s_addc_u32 s29, s29, 0
	s_add_u32 s51, s51, 0x100
	s_addc_u32 s52, s52, 0
	s_cmp_gt_u32 s53, 29
	s_cbranch_scc0 .LBB0_1126
	s_and_b64 vcc, exec, s[14:15]
	s_cbranch_vccz .LBB0_1129
	s_barrier
